# g3: hoist item-invariant gla_norm_w loads out of the item loop (on scan rebalance + priorities + wide stores + read split)
# speedup vs baseline: 1.0083x; 1.0042x over previous
; DI void gla_g3_block(const P& p, int cgi, int hh, char* smem) {
;     ...
;       const float gw = p.gla_norm_w[v];
; DI void phase_g3_combine(const P& p, char* smem_block) {
;   _Pragma("nounroll") for (int rp = 0; rp < REPG3; ++rp)
;   for (int it = blockIdx.x; it < NCHUNK * 4; it += gridDim.x) gla_g3_block(p, it >> 2, it & 3, smem_block);
.LBB0_566:
	s_mov_b64 s[4:5], s[0:1]
	v_mov_b32_e32 v35, 0
	global_load_dwordx4 v[0:3], v35, s[4:5] offset:80
	global_load_dwordx4 v[4:7], v35, s[4:5] offset:96
	global_load_dwordx4 v[8:11], v35, s[4:5] offset:112
	global_load_dwordx4 v[12:15], v35, s[4:5] offset:232
	s_add_u32 s12, s0, 0x100
	s_addc_u32 s13, s1, 0
	s_cmpk_gt_i32 s2, 0x13ff
	v_and_b32_e32 v32, 15, v210
	s_waitcnt vmcnt(0)
	v_readfirstlane_b32 s5, v1
	v_readfirstlane_b32 s4, v0
	v_readfirstlane_b32 s25, v3
	v_readfirstlane_b32 s24, v2
	v_readfirstlane_b32 s27, v5
	v_readfirstlane_b32 s26, v4
	v_readfirstlane_b32 s29, v7
	v_readfirstlane_b32 s28, v6
	v_readfirstlane_b32 s31, v9
	v_readfirstlane_b32 s30, v8
	v_readfirstlane_b32 s17, v11
	v_readfirstlane_b32 s16, v10
	v_readfirstlane_b32 s35, v13
	v_readfirstlane_b32 s34, v12
	v_readfirstlane_b32 s11, v15
	v_readfirstlane_b32 s10, v14
	s_cbranch_scc1 .LBB0_575
	s_add_i32 s6, 16, 0x12000
	s_add_u32 s36, s34, 0x2800000
	v_bfe_u32 v1, v210, 4, 2
	v_lshrrev_b32_e32 v33, 3, v210
	s_addc_u32 s37, s35, 0
	v_and_b32_e32 v0, 7, v210
	s_movk_i32 s33, 0x90
	v_lshlrev_b32_e32 v37, 2, v1
	v_lshlrev_b32_e32 v39, 4, v1
	v_mov_b32_e32 v1, s6
	s_add_u32 s38, s34, 0x5000000
	v_lshlrev_b32_e32 v34, 7, v33
	v_lshlrev_b32_e32 v36, 3, v0
	v_lshlrev_b32_e32 v0, 4, v0
	v_mad_u32_u24 v67, v32, s33, v1
	s_addc_u32 s39, s35, 0
	v_lshl_add_u64 v[4:5], s[10:11], 0, v[34:35]
	v_mov_b32_e32 v1, v35
	v_mad_u32_u24 v6, v33, s33, v0
	v_add_u32_e32 v7, s6, v39
	v_lshlrev_b32_e32 v2, 2, v32
	s_add_u32 s40, s34, 0x7800000
	v_lshl_add_u64 v[0:1], v[4:5], 0, v[0:1]
	s_mov_b64 s[6:7], 0x2ab00000
	v_lshlrev_b32_e32 v34, 1, v32
	v_mov_b32_e32 v3, v35
	s_addc_u32 s41, s35, 0
	v_lshl_add_u64 v[40:41], v[0:1], 0, s[6:7]
	v_lshl_add_u64 v[0:1], s[10:11], 0, v[34:35]
	s_mov_b64 s[6:7], 0x16100000
	v_lshl_add_u64 v[44:45], s[4:5], 0, v[2:3]
	s_mov_b64 s[4:5], 0x1b100000
	v_mul_u32_u24_e32 v62, 0x90, v32
	v_or_b32_e32 v66, 64, v39
	v_add_u32_e32 v8, 0x900, v67
	v_add_u32_e32 v9, 0x1200, v67
	v_add_u32_e32 v10, 0x1b00, v67
	v_add_u32_e32 v11, 0x2400, v67
	v_add_u32_e32 v12, 0x2d00, v67
	v_add_u32_e32 v13, 0x3600, v67
	v_add_u32_e32 v14, 0x3f00, v67
	s_add_u32 s42, s10, 0x11100000
	v_lshl_add_u64 v[42:43], v[0:1], 0, s[6:7]
	v_lshl_add_u64 v[46:47], v[0:1], 0, s[4:5]
	v_add_u32_e32 v68, 16, v6
	v_mbcnt_lo_u32_b32 v0, -1, 0
	v_or_b32_e32 v63, 16, v32
	v_or_b32_e32 v64, 32, v32
	v_or_b32_e32 v65, 48, v32
	v_add_u32_e32 v38, 16, v2
	s_addc_u32 s43, s11, 0
	s_movk_i32 s47, 0x2000
	s_mov_b32 s45, 0
	s_movk_i32 s49, 0x4000
	s_movk_i32 s52, 0x6000
	s_mov_b32 s53, 0xa00000
	v_add_u32_e32 v69, v7, v62
	v_add_u32_e32 v70, v8, v66
	v_add_u32_e32 v71, v9, v66
	v_add_u32_e32 v72, v10, v66
	v_add_u32_e32 v73, v11, v66
	v_add_u32_e32 v74, v12, v66
	v_add_u32_e32 v75, v13, v66
	v_add_u32_e32 v76, v14, v66
	s_movk_i32 s54, 0x210
	s_brev_b32 s46, 60
	s_mov_b32 s48, 0x358637bd
	s_mov_b32 s55, 0x800000
	v_lshlrev_b32_e32 v48, 1, v36
	v_mov_b32_e32 v49, v35
	v_add_u32_e32 v77, 0x12000, v68
	v_add_u32_e32 v78, 0x14400, v68
	v_mbcnt_hi_u32_b32 v79, -1, v0
	global_load_dword v165, v[44:45], off
	global_load_dword v166, v[44:45], off offset:64
	global_load_dword v167, v[44:45], off offset:128
	global_load_dword v168, v[44:45], off offset:192
	global_load_dword v169, v[44:45], off offset:256
	global_load_dword v170, v[44:45], off offset:320
	global_load_dword v171, v[44:45], off offset:384
	global_load_dword v172, v[44:45], off offset:448
	s_waitcnt vmcnt(0)
	s_mov_b32 s56, s2
	s_branch .LBB0_569

; DI void gla_g3_block(const P& p, int cgi, int hh, char* smem) {
;     ...
;   if (dir == 0) {
; #pragma unroll
;     for (int j = 0; j < 8; ++j)
; #pragma unroll
;       for (int r = 0; r < 4; ++r) o[j][r] += ob[(16 * slab + 4 * q4 + r) * 132 + 16 * j + r16];
;     float ss[4];
; #pragma unroll
;     for (int r = 0; r < 4; ++r) {
;       float sq = 0.f;
; #pragma unroll
;       for (int j = 0; j < 8; ++j) sq += o[j][r] * o[j][r];
;       sq += __shfl_xor(sq, 1); sq += __shfl_xor(sq, 2); sq += __shfl_xor(sq, 4); sq += __shfl_xor(sq, 8);
;       ss[r] = rsqrtf(sq * (1.f / 128.f) + EPS);
.LBB0_573:
	s_andn2_b64 vcc, exec, vcc
	s_waitcnt lgkmcnt(0)
	s_barrier
	s_cbranch_vccnz .LBB0_568
	v_or_b32_e32 v140, s6, v37
	v_mad_u64_u32 v[50:51], s[4:5], v140, s54, v[38:39]
	ds_read2_b32 v[112:113], v50 offset1:16
	ds_read2_b32 v[114:115], v50 offset0:132 offset1:148
	v_add_u32_e32 v51, 0x400, v50
	ds_read2_b32 v[116:117], v51 offset0:8 offset1:24
	ds_read2_b32 v[118:119], v51 offset0:140 offset1:156
	ds_read2_b32 v[52:53], v50 offset0:32 offset1:48
	ds_read2_b32 v[56:57], v50 offset0:164 offset1:180
	ds_read2_b32 v[120:121], v51 offset0:40 offset1:56
	ds_read2_b32 v[122:123], v51 offset0:172 offset1:188
	ds_read2_b32 v[124:125], v50 offset0:64 offset1:80
	ds_read2_b32 v[126:127], v50 offset0:196 offset1:212
	ds_read2_b32 v[128:129], v51 offset0:72 offset1:88
	ds_read2_b32 v[58:59], v51 offset0:204 offset1:220
	ds_read2_b32 v[130:131], v50 offset0:96 offset1:112
	ds_read2_b32 v[132:133], v50 offset0:228 offset1:244
	ds_read2_b32 v[134:135], v51 offset0:104 offset1:120
	ds_read2_b32 v[60:61], v51 offset0:236 offset1:252
	v_and_b32_e32 v51, 64, v79
	v_xor_b32_e32 v50, 1, v79
	v_add_u32_e32 v111, 64, v51
	v_cmp_lt_i32_e32 vcc, v50, v111
	v_mov_b32_e32 v51, v28
	v_mov_b32_e32 v28, v25
	v_cndmask_b32_e32 v50, v79, v50, vcc
	v_lshlrev_b32_e32 v141, 2, v50
	v_mov_b32_e32 v50, v24
	s_waitcnt lgkmcnt(10)
	v_pk_add_f32 v[24:25], v[28:29], v[56:57]
	v_mov_b32_e32 v28, v112
	v_mov_b32_e32 v29, v114
	v_mov_b32_e32 v114, v113
	v_pk_add_f32 v[54:55], v[50:51], v[52:53]
	v_pk_add_f32 v[56:57], v[16:17], v[28:29]
	v_pk_add_f32 v[28:29], v[12:13], v[114:115]
	v_pk_mul_f32 v[136:137], v[54:55], v[54:55]
	v_mov_b32_e32 v50, v20
	v_mov_b32_e32 v51, v4
	v_pk_mul_f32 v[138:139], v[24:25], v[24:25]
	v_pk_mul_f32 v[12:13], v[28:29], v[28:29]
	v_mov_b32_e32 v4, v21
	s_waitcnt lgkmcnt(7)
	v_pk_add_f32 v[52:53], v[50:51], v[124:125]
	v_pk_fma_f32 v[16:17], v[56:57], v[56:57], v[12:13]
	s_waitcnt lgkmcnt(6)
	v_pk_add_f32 v[12:13], v[4:5], v[126:127]
	v_mov_b32_e32 v20, v138
	v_mov_b32_e32 v21, v136
	v_pk_mul_f32 v[124:125], v[52:53], v[52:53]
	v_mov_b32_e32 v50, v8
	v_mov_b32_e32 v51, v0
	v_pk_mul_f32 v[4:5], v[12:13], v[12:13]
	v_mov_b32_e32 v0, v9
	v_pk_add_f32 v[16:17], v[16:17], v[20:21] op_sel:[1,0] op_sel_hi:[0,1]
	v_mov_b32_e32 v136, v139
	s_waitcnt lgkmcnt(3)
	v_pk_add_f32 v[50:51], v[50:51], v[130:131]
	s_waitcnt lgkmcnt(2)
	v_pk_add_f32 v[0:1], v[0:1], v[132:133]
	v_pk_add_f32 v[16:17], v[16:17], v[136:137]
	v_mov_b32_e32 v20, v4
	v_mov_b32_e32 v21, v124
	v_pk_mul_f32 v[130:131], v[50:51], v[50:51]
	v_pk_mul_f32 v[8:9], v[0:1], v[0:1]
	v_pk_add_f32 v[16:17], v[16:17], v[20:21]
	v_mov_b32_e32 v124, v5
	v_pk_add_f32 v[4:5], v[16:17], v[124:125]
	v_mov_b32_e32 v16, v8
	v_mov_b32_e32 v17, v130
	v_pk_add_f32 v[4:5], v[4:5], v[16:17]
	v_mov_b32_e32 v130, v9
	v_pk_add_f32 v[4:5], v[4:5], v[130:131]
	ds_bpermute_b32 v9, v141, v5
	ds_bpermute_b32 v8, v141, v4
	v_mov_b32_e32 v113, v165
	v_xor_b32_e32 v16, 2, v79
	v_cmp_lt_i32_e32 vcc, v16, v111
	s_lshl_b32 s44, s57, 1
	s_waitcnt lgkmcnt(0)
	v_pk_add_f32 v[4:5], v[4:5], v[8:9]
	v_cndmask_b32_e32 v16, v79, v16, vcc
	v_lshlrev_b32_e32 v112, 2, v16
	ds_bpermute_b32 v9, v112, v5
	ds_bpermute_b32 v8, v112, v4
	v_xor_b32_e32 v16, 4, v79
	v_cmp_lt_i32_e32 vcc, v16, v111
	s_waitcnt lgkmcnt(0)
	v_pk_add_f32 v[4:5], v[4:5], v[8:9]
	v_cndmask_b32_e32 v16, v79, v16, vcc
	v_lshlrev_b32_e32 v130, 2, v16
	ds_bpermute_b32 v9, v130, v5
	ds_bpermute_b32 v8, v130, v4
	v_xor_b32_e32 v16, 8, v79
	v_cmp_lt_i32_e32 vcc, v16, v111
	s_waitcnt lgkmcnt(0)
	v_pk_add_f32 v[114:115], v[4:5], v[8:9]
	v_mov_b32_e32 v5, v30
	v_mov_b32_e32 v30, v27
	v_cndmask_b32_e32 v16, v79, v16, vcc
	v_mov_b32_e32 v4, v26
	v_pk_add_f32 v[20:21], v[30:31], v[122:123]
	v_mov_b32_e32 v31, v118
	v_mov_b32_e32 v118, v117
	v_lshlrev_b32_e32 v111, 2, v16
	v_pk_add_f32 v[16:17], v[4:5], v[120:121]
	v_mov_b32_e32 v30, v116
	v_pk_add_f32 v[14:15], v[14:15], v[118:119]
	v_pk_mul_f32 v[120:121], v[16:17], v[16:17]
	v_mov_b32_e32 v4, v22
	v_mov_b32_e32 v5, v6
	v_pk_mul_f32 v[26:27], v[20:21], v[20:21]
	v_pk_add_f32 v[18:19], v[18:19], v[30:31]
	v_pk_mul_f32 v[30:31], v[14:15], v[14:15]
	v_mov_b32_e32 v6, v23
	v_pk_add_f32 v[8:9], v[4:5], v[128:129]
	v_pk_fma_f32 v[30:31], v[18:19], v[18:19], v[30:31]
	v_pk_add_f32 v[6:7], v[6:7], v[58:59]
	v_mov_b32_e32 v58, v26
	v_mov_b32_e32 v59, v120
	v_pk_mul_f32 v[126:127], v[8:9], v[8:9]
	v_mov_b32_e32 v4, v10
	v_mov_b32_e32 v5, v2
	v_pk_mul_f32 v[22:23], v[6:7], v[6:7]
	v_mov_b32_e32 v2, v11
	v_pk_add_f32 v[30:31], v[30:31], v[58:59] op_sel:[1,0] op_sel_hi:[0,1]
	v_mov_b32_e32 v120, v27
	v_pk_add_f32 v[4:5], v[4:5], v[134:135]
	v_pk_add_f32 v[2:3], v[2:3], v[60:61]
	v_pk_add_f32 v[26:27], v[30:31], v[120:121]
	v_mov_b32_e32 v30, v22
	v_mov_b32_e32 v31, v126
	v_pk_mul_f32 v[128:129], v[4:5], v[4:5]
	v_pk_mul_f32 v[10:11], v[2:3], v[2:3]
	v_pk_add_f32 v[26:27], v[26:27], v[30:31]
	v_mov_b32_e32 v126, v23
	v_pk_add_f32 v[22:23], v[26:27], v[126:127]
	v_mov_b32_e32 v26, v10
	v_mov_b32_e32 v27, v128
	v_pk_add_f32 v[22:23], v[22:23], v[26:27]
	v_mov_b32_e32 v128, v11
	v_pk_add_f32 v[10:11], v[22:23], v[128:129]
	ds_bpermute_b32 v23, v141, v11
	ds_bpermute_b32 v22, v141, v10
	ds_bpermute_b32 v125, v111, v115
	ds_bpermute_b32 v124, v111, v114
	v_mov_b64_e32 v[30:31], s[48:49]
	s_waitcnt lgkmcnt(2)
	v_pk_add_f32 v[10:11], v[10:11], v[22:23]
	ds_bpermute_b32 v23, v112, v11
	ds_bpermute_b32 v22, v112, v10
	s_waitcnt lgkmcnt(2)
	v_pk_add_f32 v[26:27], v[114:115], v[124:125]
	s_waitcnt lgkmcnt(0)
	v_pk_add_f32 v[10:11], v[10:11], v[22:23]
	ds_bpermute_b32 v23, v130, v11
	ds_bpermute_b32 v22, v130, v10
	v_pk_fma_f32 v[26:27], v[26:27], s[46:47], v[30:31] op_sel_hi:[1,0,0]
	s_waitcnt lgkmcnt(0)
; DI float b2f(unsigned b) { return __uint_as_float(b << 16); }
; DI float fexp(float x) { return __builtin_amdgcn_exp2f(x * LOG2E); }
; DI void gla_g3_block(const P& p, int cgi, int hh, char* smem) {
;     ...
;       ss[r] = rsqrtf(sq * (1.f / 128.f) + EPS);
;     }
;     bf16_t* mixin = (bf16_t*)(p.ws + OFF_MIXIN);
; #pragma unroll
;     for (int j = 0; j < 8; ++j) {
;       const int v = 16 * j + r16;
;       const float gw = p.gla_norm_w[v];
; #pragma unroll
;       for (int r = 0; r < 4; ++r) {
;         const int tok = t0 + 16 * slab + 4 * q4 + r;
;         float g = b2f(graw[j][r]);
;         float val = o[j][r] * ss[r] * gw * (g / (1.f + fexp(-g)));
;         mixin[(long)tok * 1024 + hh * 128 + v] = f2b(val);
	v_pk_add_f32 v[10:11], v[10:11], v[22:23]
	v_mul_f32_e32 v58, 0x4b800000, v27
	v_cmp_gt_f32_e32 vcc, s55, v27
	ds_bpermute_b32 v23, v111, v11
	ds_bpermute_b32 v22, v111, v10
	v_cndmask_b32_e32 v27, v27, v58, vcc
	v_rsq_f32_e32 v27, v27
	v_mul_f32_e32 v58, 0x4b800000, v26
	v_cmp_gt_f32_e64 s[4:5], s55, v26
	s_waitcnt lgkmcnt(0)
	v_pk_add_f32 v[10:11], v[10:11], v[22:23]
	v_cndmask_b32_e64 v26, v26, v58, s[4:5]
	v_mul_f32_e32 v58, 0x45800000, v27
	v_pk_fma_f32 v[10:11], v[10:11], s[46:47], v[30:31] op_sel_hi:[1,0,0]
	v_cndmask_b32_e32 v112, v27, v58, vcc
	v_mul_f32_e32 v22, 0x4b800000, v11
	v_cmp_gt_f32_e32 vcc, s55, v11
	v_cmp_gt_f32_e64 s[6:7], s55, v10
	v_rsq_f32_e32 v26, v26
	v_cndmask_b32_e32 v11, v11, v22, vcc
	v_mul_f32_e32 v22, 0x4b800000, v10
	v_rsq_f32_e32 v11, v11
	v_cndmask_b32_e64 v10, v10, v22, s[6:7]
	v_rsq_f32_e32 v10, v10
	v_mul_f32_e32 v27, 0x45800000, v26
	v_mul_f32_e32 v22, 0x45800000, v11
	v_cndmask_b32_e32 v61, v11, v22, vcc
	v_mul_f32_e32 v11, 0x45800000, v10
	v_cndmask_b32_e64 v60, v10, v11, s[6:7]
	v_mul_f32_e32 v10, 0xbfb8aa3b, v110
	v_exp_f32_e32 v23, v10
	v_cndmask_b32_e64 v111, v26, v27, s[4:5]
	v_mul_f32_e32 v30, v56, v112
	s_waitcnt vmcnt(0)
	v_mul_f32_e32 v30, v30, v113
	v_add_f32_e32 v23, 1.0, v23
	v_div_scale_f32 v27, s[4:5], v23, v23, v110
	v_rcp_f32_e32 v26, v27
	v_or_b32_e32 v22, s50, v140
	v_and_b32_e32 v156, 48, v140
	v_bfe_u32 v157, v140, 2, 2
	v_and_b32_e32 v158, 15, v79
	v_mul_u32_u24_e32 v159, 0x210, v156
	v_add_u32_e32 v159, 16, v159
	v_mul_u32_u24_e32 v160, 0x440, v157
	v_lshl_add_u32 v200, v158, 1, v159
	v_add_u32_e32 v200, v200, v160
	v_mul_u32_u24_e32 v160, 0x110, v157
	v_lshl_add_u32 v201, v158, 4, v159
	v_add_u32_e32 v201, v201, v160
	v_add3_u32 v161, s50, v156, v157
	v_mov_b32_e32 v163, 0
	v_lshlrev_b32_e32 v162, 11, v161
	v_mul_u32_u24_e32 v164, 14, v158
	v_lshl_add_u64 v[202:203], v[46:47], 0, s[44:45]
	v_add_u32_e32 v162, v162, v164
	v_lshl_add_u64 v[202:203], v[202:203], 0, v[162:163]
	v_mov_b32_e32 v56, v166
	v_mov_b32_e32 v114, v167
	v_mov_b32_e32 v115, v168
	v_mov_b32_e32 v116, v169
	v_mov_b32_e32 v118, v170
	v_mov_b32_e32 v119, v171
	v_mov_b32_e32 v117, v172
	v_lshl_add_u64 v[10:11], v[46:47], 0, s[44:45]
	v_fma_f32 v31, -v27, v26, 1.0
	v_fmac_f32_e32 v26, v31, v26
	v_div_scale_f32 v31, vcc, v110, v23, v110
	v_mul_f32_e32 v58, v31, v26
	v_fma_f32 v59, -v27, v58, v31
	v_fmac_f32_e32 v58, v59, v26
	v_fma_f32 v27, -v27, v58, v31
	v_div_fmas_f32 v26, v27, v26, v58
	v_div_fixup_f32 v23, v26, v23, v110
	v_mul_f32_e32 v26, 0xbfb8aa3b, v109
	v_exp_f32_e32 v31, v26
	v_mul_f32_e32 v23, v23, v30
	v_cvt_pk_bf16_f32 v30, v23, s0
	v_ashrrev_i32_e32 v23, 31, v22
	v_lshlrev_b64 v[26:27], 11, v[22:23]
	v_add_f32_e32 v23, 1.0, v31
	v_lshl_add_u64 v[58:59], v[10:11], 0, v[26:27]
	v_div_scale_f32 v27, s[4:5], v23, v23, v109
	ds_write_b16 v200, v30 offset:0
	v_rcp_f32_e32 v30, v27
	v_mul_f32_e32 v31, v57, v111
	v_or_b32_e32 v26, 1, v22
	v_mul_f32_e32 v31, v113, v31
	v_fma_f32 v57, -v27, v30, 1.0
	v_fmac_f32_e32 v30, v57, v30
	v_div_scale_f32 v57, vcc, v109, v23, v109
	v_mul_f32_e32 v110, v57, v30
	v_fma_f32 v120, -v27, v110, v57
	v_fmac_f32_e32 v110, v120, v30
	v_fma_f32 v27, -v27, v110, v57
	v_div_fmas_f32 v27, v27, v30, v110
	v_mul_f32_e32 v30, 0xbfb8aa3b, v108
	v_exp_f32_e32 v57, v30
	v_div_fixup_f32 v23, v27, v23, v109
	v_ashrrev_i32_e32 v27, 31, v26
	v_mul_f32_e32 v23, v23, v31
	v_lshlrev_b64 v[26:27], 11, v[26:27]
	v_cvt_pk_bf16_f32 v23, v23, s0
	v_lshl_add_u64 v[30:31], v[10:11], 0, v[26:27]
	ds_write_b16 v200, v23 offset:272
	v_add_f32_e32 v23, 1.0, v57
	v_div_scale_f32 v27, s[4:5], v23, v23, v108
	v_rcp_f32_e32 v57, v27
	v_mul_f32_e32 v18, v18, v61
	v_mul_f32_e32 v18, v113, v18
	v_or_b32_e32 v26, 2, v22
	v_fma_f32 v109, -v27, v57, 1.0
	v_fmac_f32_e32 v57, v109, v57
	v_div_scale_f32 v109, vcc, v108, v23, v108
	v_mul_f32_e32 v110, v109, v57
	v_fma_f32 v120, -v27, v110, v109
	v_fmac_f32_e32 v110, v120, v57
	v_fma_f32 v27, -v27, v110, v109
	v_div_fmas_f32 v27, v27, v57, v110
	v_div_fixup_f32 v23, v27, v23, v108
	v_mul_f32_e32 v18, v23, v18
	v_mul_f32_e32 v23, 0xbfb8aa3b, v107
	v_exp_f32_e32 v23, v23
	v_ashrrev_i32_e32 v27, 31, v26
	v_lshlrev_b64 v[26:27], 11, v[26:27]
	v_cvt_pk_bf16_f32 v18, v18, s0
	v_add_f32_e32 v23, 1.0, v23
	v_div_scale_f32 v57, s[4:5], v23, v23, v107
	v_rcp_f32_e32 v108, v57
	v_lshl_add_u64 v[26:27], v[10:11], 0, v[26:27]
	ds_write_b16 v200, v18 offset:544
	v_or_b32_e32 v18, 3, v22
	v_fma_f32 v22, -v57, v108, 1.0
	v_fmac_f32_e32 v108, v22, v108
	v_div_scale_f32 v22, vcc, v107, v23, v107
	v_mul_f32_e32 v109, v22, v108
	v_fma_f32 v110, -v57, v109, v22
	v_fmac_f32_e32 v109, v110, v108
	v_fma_f32 v22, -v57, v109, v22
	v_mul_f32_e32 v19, v19, v60
	v_div_fmas_f32 v22, v22, v108, v109
	v_mul_f32_e32 v19, v113, v19
	v_div_fixup_f32 v22, v22, v23, v107
	v_mul_f32_e32 v19, v22, v19
	v_cvt_pk_bf16_f32 v22, v19, s0
	v_mul_f32_e32 v19, 0xbfb8aa3b, v106
	v_exp_f32_e32 v23, v19
	v_ashrrev_i32_e32 v19, 31, v18
	v_lshlrev_b64 v[18:19], 11, v[18:19]
	v_lshl_add_u64 v[10:11], v[10:11], 0, v[18:19]
	v_add_f32_e32 v18, 1.0, v23
	v_div_scale_f32 v19, s[4:5], v18, v18, v106
	v_rcp_f32_e32 v23, v19
	ds_write_b16 v200, v22 offset:816
	v_mul_f32_e32 v22, v28, v112
	s_waitcnt vmcnt(0)
; DI float b2f(unsigned b) { return __uint_as_float(b << 16); }
; DI float fexp(float x) { return __builtin_amdgcn_exp2f(x * LOG2E); }
; DI void gla_g3_block(const P& p, int cgi, int hh, char* smem) {
;     ...
;     for (int j = 0; j < 8; ++j) {
;       const int v = 16 * j + r16;
;       const float gw = p.gla_norm_w[v];
; #pragma unroll
;       for (int r = 0; r < 4; ++r) {
;         const int tok = t0 + 16 * slab + 4 * q4 + r;
;         float g = b2f(graw[j][r]);
;         float val = o[j][r] * ss[r] * gw * (g / (1.f + fexp(-g)));
;         mixin[(long)tok * 1024 + hh * 128 + v] = f2b(val);
	v_mul_f32_e32 v22, v22, v56
	v_fma_f32 v28, -v19, v23, 1.0
	v_fmac_f32_e32 v23, v28, v23
	v_div_scale_f32 v28, vcc, v106, v18, v106
	v_mul_f32_e32 v57, v28, v23
	v_fma_f32 v107, -v19, v57, v28
	v_fmac_f32_e32 v57, v107, v23
	v_fma_f32 v19, -v19, v57, v28
	v_div_fmas_f32 v19, v19, v23, v57
	v_mul_f32_e32 v23, 0xbfb8aa3b, v105
	v_exp_f32_e32 v23, v23
	v_div_fixup_f32 v18, v19, v18, v106
	v_mul_f32_e32 v18, v18, v22
	v_cvt_pk_bf16_f32 v18, v18, s0
	v_add_f32_e32 v19, 1.0, v23
	v_div_scale_f32 v22, s[4:5], v19, v19, v105
	v_rcp_f32_e32 v23, v22
	ds_write_b16 v200, v18 offset:32
	v_mul_f32_e32 v18, v29, v111
	v_mul_f32_e32 v18, v18, v56
	v_fma_f32 v28, -v22, v23, 1.0
	v_fmac_f32_e32 v23, v28, v23
	v_div_scale_f32 v28, vcc, v105, v19, v105
	v_mul_f32_e32 v29, v28, v23
	v_fma_f32 v57, -v22, v29, v28
	v_fmac_f32_e32 v29, v57, v23
	v_fma_f32 v22, -v22, v29, v28
	v_div_fmas_f32 v22, v22, v23, v29
	v_mul_f32_e32 v23, 0xbfb8aa3b, v104
	v_exp_f32_e32 v23, v23
	v_div_fixup_f32 v19, v22, v19, v105
	v_mul_f32_e32 v18, v19, v18
	v_cvt_pk_bf16_f32 v18, v18, s0
	v_add_f32_e32 v19, 1.0, v23
	v_div_scale_f32 v22, s[4:5], v19, v19, v104
	v_rcp_f32_e32 v23, v22
	ds_write_b16 v200, v18 offset:304
	v_mul_f32_e32 v14, v14, v61
	v_mul_f32_e32 v14, v14, v56
	v_fma_f32 v18, -v22, v23, 1.0
	v_fmac_f32_e32 v23, v18, v23
	v_div_scale_f32 v18, vcc, v104, v19, v104
	v_mul_f32_e32 v28, v18, v23
	v_fma_f32 v29, -v22, v28, v18
	v_fmac_f32_e32 v28, v29, v23
	v_fma_f32 v18, -v22, v28, v18
	v_mul_f32_e32 v22, 0xbfb8aa3b, v103
	v_exp_f32_e32 v22, v22
	v_div_fmas_f32 v18, v18, v23, v28
	v_div_fixup_f32 v18, v18, v19, v104
	v_mul_f32_e32 v14, v18, v14
	v_add_f32_e32 v18, 1.0, v22
	v_div_scale_f32 v19, s[4:5], v18, v18, v103
	v_rcp_f32_e32 v22, v19
	v_cvt_pk_bf16_f32 v14, v14, s0
	ds_write_b16 v200, v14 offset:576
	v_mul_f32_e32 v14, v15, v60
	v_fma_f32 v15, -v19, v22, 1.0
	v_fmac_f32_e32 v22, v15, v22
	v_div_scale_f32 v15, vcc, v103, v18, v103
	v_mul_f32_e32 v23, v15, v22
	v_fma_f32 v28, -v19, v23, v15
	v_fmac_f32_e32 v23, v28, v22
	v_fma_f32 v15, -v19, v23, v15
	v_mul_f32_e32 v19, 0xbfb8aa3b, v102
	v_exp_f32_e32 v19, v19
	v_div_fmas_f32 v15, v15, v22, v23
	v_mul_f32_e32 v14, v56, v14
	v_div_fixup_f32 v15, v15, v18, v103
	v_mul_f32_e32 v14, v15, v14
	v_add_f32_e32 v15, 1.0, v19
	v_div_scale_f32 v18, s[4:5], v15, v15, v102
	v_rcp_f32_e32 v19, v18
	v_cvt_pk_bf16_f32 v14, v14, s0
	ds_write_b16 v200, v14 offset:848
	v_mul_f32_e32 v14, v54, v112
	v_fma_f32 v22, -v18, v19, 1.0
	v_fmac_f32_e32 v19, v22, v19
	v_div_scale_f32 v22, vcc, v102, v15, v102
	v_mul_f32_e32 v23, v22, v19
	v_fma_f32 v28, -v18, v23, v22
	v_fmac_f32_e32 v23, v28, v19
	v_fma_f32 v18, -v18, v23, v22
	v_div_fmas_f32 v18, v18, v19, v23
	v_mul_f32_e32 v19, 0xbfb8aa3b, v101
	v_exp_f32_e32 v19, v19
	s_waitcnt vmcnt(0)
	v_mul_f32_e32 v14, v14, v114
	v_div_fixup_f32 v15, v18, v15, v102
	v_mul_f32_e32 v14, v15, v14
	v_add_f32_e32 v15, 1.0, v19
	v_div_scale_f32 v18, s[4:5], v15, v15, v101
	v_rcp_f32_e32 v19, v18
	v_cvt_pk_bf16_f32 v14, v14, s0
	ds_write_b16 v200, v14 offset:64
	v_mul_f32_e32 v14, v24, v111
	v_fma_f32 v22, -v18, v19, 1.0
	v_fmac_f32_e32 v19, v22, v19
	v_div_scale_f32 v22, vcc, v101, v15, v101
	v_mul_f32_e32 v23, v22, v19
	v_fma_f32 v24, -v18, v23, v22
	v_fmac_f32_e32 v23, v24, v19
	v_fma_f32 v18, -v18, v23, v22
	v_div_fmas_f32 v18, v18, v19, v23
	v_mul_f32_e32 v19, 0xbfb8aa3b, v100
	v_exp_f32_e32 v19, v19
	v_mul_f32_e32 v14, v14, v114
	v_div_fixup_f32 v15, v18, v15, v101
	v_mul_f32_e32 v14, v15, v14
	v_add_f32_e32 v15, 1.0, v19
	v_div_scale_f32 v18, s[4:5], v15, v15, v100
	v_rcp_f32_e32 v19, v18
	v_cvt_pk_bf16_f32 v14, v14, s0
	ds_write_b16 v200, v14 offset:336
	v_mul_f32_e32 v14, v16, v61
	v_fma_f32 v16, -v18, v19, 1.0
	v_fmac_f32_e32 v19, v16, v19
	v_div_scale_f32 v16, vcc, v100, v15, v100
	v_mul_f32_e32 v22, v16, v19
	v_fma_f32 v23, -v18, v22, v16
	v_fmac_f32_e32 v22, v23, v19
	v_fma_f32 v16, -v18, v22, v16
	v_mul_f32_e32 v18, 0xbfb8aa3b, v99
	v_exp_f32_e32 v18, v18
	v_div_fmas_f32 v16, v16, v19, v22
	v_mul_f32_e32 v14, v14, v114
	v_div_fixup_f32 v15, v16, v15, v100
	v_mul_f32_e32 v14, v15, v14
	v_add_f32_e32 v15, 1.0, v18
	v_div_scale_f32 v16, s[4:5], v15, v15, v99
	v_rcp_f32_e32 v18, v16
	v_cvt_pk_bf16_f32 v14, v14, s0
	ds_write_b16 v200, v14 offset:608
	v_mul_f32_e32 v14, v20, v60
	v_fma_f32 v19, -v16, v18, 1.0
	v_fmac_f32_e32 v18, v19, v18
	v_div_scale_f32 v19, vcc, v99, v15, v99
	v_mul_f32_e32 v20, v19, v18
	v_fma_f32 v22, -v16, v20, v19
	v_fmac_f32_e32 v20, v22, v18
	v_fma_f32 v16, -v16, v20, v19
	v_div_fmas_f32 v16, v16, v18, v20
	v_mul_f32_e32 v18, 0xbfb8aa3b, v98
	v_exp_f32_e32 v18, v18
	v_mul_f32_e32 v14, v14, v114
	v_div_fixup_f32 v15, v16, v15, v99
	v_mul_f32_e32 v14, v15, v14
	v_add_f32_e32 v15, 1.0, v18
	v_div_scale_f32 v16, s[4:5], v15, v15, v98
	v_rcp_f32_e32 v18, v16
	v_cvt_pk_bf16_f32 v14, v14, s0
	ds_write_b16 v200, v14 offset:880
	v_mul_f32_e32 v14, v55, v112
	v_fma_f32 v19, -v16, v18, 1.0
	v_fmac_f32_e32 v18, v19, v18
	v_div_scale_f32 v19, vcc, v98, v15, v98
	v_mul_f32_e32 v20, v19, v18
	v_fma_f32 v22, -v16, v20, v19
	v_fmac_f32_e32 v20, v22, v18
	v_fma_f32 v16, -v16, v20, v19
	v_div_fmas_f32 v16, v16, v18, v20
	v_mul_f32_e32 v18, 0xbfb8aa3b, v97
	v_exp_f32_e32 v18, v18
	s_waitcnt vmcnt(0)
; DI float b2f(unsigned b) { return __uint_as_float(b << 16); }
; DI float fexp(float x) { return __builtin_amdgcn_exp2f(x * LOG2E); }
; DI void gla_g3_block(const P& p, int cgi, int hh, char* smem) {
;     ...
;     for (int j = 0; j < 8; ++j) {
;       const int v = 16 * j + r16;
;       const float gw = p.gla_norm_w[v];
; #pragma unroll
;       for (int r = 0; r < 4; ++r) {
;         const int tok = t0 + 16 * slab + 4 * q4 + r;
;         float g = b2f(graw[j][r]);
;         float val = o[j][r] * ss[r] * gw * (g / (1.f + fexp(-g)));
;         mixin[(long)tok * 1024 + hh * 128 + v] = f2b(val);
	v_mul_f32_e32 v14, v14, v115
	v_div_fixup_f32 v15, v16, v15, v98
	v_mul_f32_e32 v14, v15, v14
	v_add_f32_e32 v15, 1.0, v18
	v_div_scale_f32 v16, s[4:5], v15, v15, v97
	v_rcp_f32_e32 v18, v16
	v_cvt_pk_bf16_f32 v14, v14, s0
	ds_write_b16 v200, v14 offset:96
	v_mul_f32_e32 v14, v25, v111
	v_fma_f32 v19, -v16, v18, 1.0
	v_fmac_f32_e32 v18, v19, v18
	v_div_scale_f32 v19, vcc, v97, v15, v97
	v_mul_f32_e32 v20, v19, v18
	v_fma_f32 v22, -v16, v20, v19
	v_fmac_f32_e32 v20, v22, v18
	v_fma_f32 v16, -v16, v20, v19
	v_div_fmas_f32 v16, v16, v18, v20
	v_mul_f32_e32 v18, 0xbfb8aa3b, v96
	v_exp_f32_e32 v18, v18
	v_mul_f32_e32 v14, v14, v115
	v_div_fixup_f32 v15, v16, v15, v97
	v_mul_f32_e32 v14, v15, v14
	v_add_f32_e32 v15, 1.0, v18
	v_div_scale_f32 v16, s[4:5], v15, v15, v96
	v_rcp_f32_e32 v18, v16
	v_cvt_pk_bf16_f32 v14, v14, s0
	ds_write_b16 v200, v14 offset:368
	v_mul_f32_e32 v14, v17, v61
	v_fma_f32 v17, -v16, v18, 1.0
	v_fmac_f32_e32 v18, v17, v18
	v_div_scale_f32 v17, vcc, v96, v15, v96
	v_mul_f32_e32 v19, v17, v18
	v_fma_f32 v20, -v16, v19, v17
	v_fmac_f32_e32 v19, v20, v18
	v_fma_f32 v16, -v16, v19, v17
	v_mul_f32_e32 v17, 0xbfb8aa3b, v95
	v_exp_f32_e32 v17, v17
	v_div_fmas_f32 v16, v16, v18, v19
	v_mul_f32_e32 v14, v14, v115
	v_div_fixup_f32 v15, v16, v15, v96
	v_mul_f32_e32 v14, v15, v14
	v_add_f32_e32 v15, 1.0, v17
	v_div_scale_f32 v16, s[4:5], v15, v15, v95
	v_rcp_f32_e32 v17, v16
	v_cvt_pk_bf16_f32 v14, v14, s0
	ds_write_b16 v200, v14 offset:640
	v_mul_f32_e32 v14, v21, v60
	v_fma_f32 v18, -v16, v17, 1.0
	v_fmac_f32_e32 v17, v18, v17
	v_div_scale_f32 v18, vcc, v95, v15, v95
	v_mul_f32_e32 v19, v18, v17
	v_fma_f32 v20, -v16, v19, v18
	v_fmac_f32_e32 v19, v20, v17
	v_fma_f32 v16, -v16, v19, v18
	v_div_fmas_f32 v16, v16, v17, v19
	v_mul_f32_e32 v17, 0xbfb8aa3b, v94
	v_exp_f32_e32 v17, v17
	v_mul_f32_e32 v14, v14, v115
	v_div_fixup_f32 v15, v16, v15, v95
	v_mul_f32_e32 v14, v15, v14
	v_add_f32_e32 v15, 1.0, v17
	v_div_scale_f32 v16, s[4:5], v15, v15, v94
	v_rcp_f32_e32 v17, v16
	v_cvt_pk_bf16_f32 v14, v14, s0
	ds_write_b16 v200, v14 offset:912
	v_mul_f32_e32 v14, v52, v112
	v_fma_f32 v18, -v16, v17, 1.0
	v_fmac_f32_e32 v17, v18, v17
	v_div_scale_f32 v18, vcc, v94, v15, v94
	v_mul_f32_e32 v19, v18, v17
	v_fma_f32 v20, -v16, v19, v18
	v_fmac_f32_e32 v19, v20, v17
	v_fma_f32 v16, -v16, v19, v18
	v_div_fmas_f32 v16, v16, v17, v19
	v_mul_f32_e32 v17, 0xbfb8aa3b, v93
	v_exp_f32_e32 v17, v17
	s_waitcnt vmcnt(0)
	v_mul_f32_e32 v14, v14, v116
	v_div_fixup_f32 v15, v16, v15, v94
	v_mul_f32_e32 v14, v15, v14
	v_add_f32_e32 v15, 1.0, v17
	v_div_scale_f32 v16, s[4:5], v15, v15, v93
	v_rcp_f32_e32 v17, v16
	v_cvt_pk_bf16_f32 v14, v14, s0
	ds_write_b16 v200, v14 offset:128
	v_mul_f32_e32 v12, v12, v111
	v_fma_f32 v14, -v16, v17, 1.0
	v_fmac_f32_e32 v17, v14, v17
	v_div_scale_f32 v14, vcc, v93, v15, v93
	v_mul_f32_e32 v18, v14, v17
	v_fma_f32 v19, -v16, v18, v14
	v_fmac_f32_e32 v18, v19, v17
	v_fma_f32 v14, -v16, v18, v14
	v_mul_f32_e32 v16, 0xbfb8aa3b, v92
	v_exp_f32_e32 v16, v16
	v_div_fmas_f32 v14, v14, v17, v18
	v_mul_f32_e32 v12, v12, v116
	v_div_fixup_f32 v14, v14, v15, v93
	v_mul_f32_e32 v12, v14, v12
	v_add_f32_e32 v14, 1.0, v16
	v_div_scale_f32 v15, s[4:5], v14, v14, v92
	v_rcp_f32_e32 v16, v15
	v_cvt_pk_bf16_f32 v12, v12, s0
	ds_write_b16 v200, v12 offset:400
	v_mul_f32_e32 v8, v8, v61
	v_fma_f32 v12, -v15, v16, 1.0
	v_fmac_f32_e32 v16, v12, v16
	v_div_scale_f32 v12, vcc, v92, v14, v92
	v_mul_f32_e32 v17, v12, v16
	v_fma_f32 v18, -v15, v17, v12
	v_fmac_f32_e32 v17, v18, v16
	v_fma_f32 v12, -v15, v17, v12
	v_mul_f32_e32 v15, 0xbfb8aa3b, v91
	v_exp_f32_e32 v15, v15
	v_div_fmas_f32 v12, v12, v16, v17
	v_mul_f32_e32 v8, v8, v116
	v_div_fixup_f32 v12, v12, v14, v92
	v_mul_f32_e32 v8, v12, v8
	v_add_f32_e32 v12, 1.0, v15
	v_div_scale_f32 v14, s[4:5], v12, v12, v91
	v_rcp_f32_e32 v15, v14
	v_cvt_pk_bf16_f32 v8, v8, s0
	ds_write_b16 v200, v8 offset:672
	v_mul_f32_e32 v6, v6, v60
	v_fma_f32 v8, -v14, v15, 1.0
	v_fmac_f32_e32 v15, v8, v15
	v_div_scale_f32 v8, vcc, v91, v12, v91
	v_mul_f32_e32 v16, v8, v15
	v_fma_f32 v17, -v14, v16, v8
	v_fmac_f32_e32 v16, v17, v15
	v_fma_f32 v8, -v14, v16, v8
	v_mul_f32_e32 v14, 0xbfb8aa3b, v90
	v_exp_f32_e32 v14, v14
	v_div_fmas_f32 v8, v8, v15, v16
	v_mul_f32_e32 v6, v6, v116
	v_div_fixup_f32 v8, v8, v12, v91
	v_mul_f32_e32 v6, v8, v6
	v_add_f32_e32 v8, 1.0, v14
	v_div_scale_f32 v12, s[4:5], v8, v8, v90
	v_rcp_f32_e32 v14, v12
	v_cvt_pk_bf16_f32 v6, v6, s0
	ds_write_b16 v200, v6 offset:944
	v_mul_f32_e32 v6, v53, v112
	v_fma_f32 v15, -v12, v14, 1.0
	v_fmac_f32_e32 v14, v15, v14
	v_div_scale_f32 v15, vcc, v90, v8, v90
	v_mul_f32_e32 v16, v15, v14
	v_fma_f32 v17, -v12, v16, v15
	v_fmac_f32_e32 v16, v17, v14
	v_fma_f32 v12, -v12, v16, v15
	v_div_fmas_f32 v12, v12, v14, v16
	v_mul_f32_e32 v14, 0xbfb8aa3b, v89
	v_exp_f32_e32 v14, v14
	s_waitcnt vmcnt(0)
; DI float b2f(unsigned b) { return __uint_as_float(b << 16); }
; DI float fexp(float x) { return __builtin_amdgcn_exp2f(x * LOG2E); }
; DI void gla_g3_block(const P& p, int cgi, int hh, char* smem) {
;     ...
;     for (int j = 0; j < 8; ++j) {
;       const int v = 16 * j + r16;
;       const float gw = p.gla_norm_w[v];
; #pragma unroll
;       for (int r = 0; r < 4; ++r) {
;         const int tok = t0 + 16 * slab + 4 * q4 + r;
;         float g = b2f(graw[j][r]);
;         float val = o[j][r] * ss[r] * gw * (g / (1.f + fexp(-g)));
;         mixin[(long)tok * 1024 + hh * 128 + v] = f2b(val);
	v_mul_f32_e32 v6, v6, v118
	v_div_fixup_f32 v8, v12, v8, v90
	v_mul_f32_e32 v6, v8, v6
	v_add_f32_e32 v8, 1.0, v14
	v_div_scale_f32 v12, s[4:5], v8, v8, v89
	v_rcp_f32_e32 v14, v12
	v_cvt_pk_bf16_f32 v6, v6, s0
	ds_write_b16 v200, v6 offset:160
	v_mul_f32_e32 v6, v13, v111
	v_fma_f32 v13, -v12, v14, 1.0
	v_fmac_f32_e32 v14, v13, v14
	v_div_scale_f32 v13, vcc, v89, v8, v89
	v_mul_f32_e32 v15, v13, v14
	v_fma_f32 v16, -v12, v15, v13
	v_fmac_f32_e32 v15, v16, v14
	v_fma_f32 v12, -v12, v15, v13
	v_mul_f32_e32 v13, 0xbfb8aa3b, v88
	v_exp_f32_e32 v13, v13
	v_div_fmas_f32 v12, v12, v14, v15
	v_mul_f32_e32 v6, v6, v118
	v_div_fixup_f32 v8, v12, v8, v89
	v_mul_f32_e32 v6, v8, v6
	v_add_f32_e32 v8, 1.0, v13
	v_div_scale_f32 v12, s[4:5], v8, v8, v88
	v_rcp_f32_e32 v13, v12
	v_cvt_pk_bf16_f32 v6, v6, s0
	ds_write_b16 v200, v6 offset:432
	v_mul_f32_e32 v6, v9, v61
	v_fma_f32 v9, -v12, v13, 1.0
	v_fmac_f32_e32 v13, v9, v13
	v_div_scale_f32 v9, vcc, v88, v8, v88
	v_mul_f32_e32 v14, v9, v13
	v_fma_f32 v15, -v12, v14, v9
	v_fmac_f32_e32 v14, v15, v13
	v_fma_f32 v9, -v12, v14, v9
	v_mul_f32_e32 v12, 0xbfb8aa3b, v87
	v_exp_f32_e32 v12, v12
	v_div_fmas_f32 v9, v9, v13, v14
	v_mul_f32_e32 v6, v6, v118
	v_div_fixup_f32 v8, v9, v8, v88
	v_mul_f32_e32 v6, v8, v6
	v_add_f32_e32 v8, 1.0, v12
	v_div_scale_f32 v9, s[4:5], v8, v8, v87
	v_rcp_f32_e32 v12, v9
	v_cvt_pk_bf16_f32 v6, v6, s0
	ds_write_b16 v200, v6 offset:704
	v_mul_f32_e32 v6, v7, v60
	v_fma_f32 v7, -v9, v12, 1.0
	v_fmac_f32_e32 v12, v7, v12
	v_div_scale_f32 v7, vcc, v87, v8, v87
	v_mul_f32_e32 v13, v7, v12
	v_fma_f32 v14, -v9, v13, v7
	v_fmac_f32_e32 v13, v14, v12
	v_fma_f32 v7, -v9, v13, v7
	v_mul_f32_e32 v9, 0xbfb8aa3b, v84
	v_exp_f32_e32 v9, v9
	v_div_fmas_f32 v7, v7, v12, v13
	v_mul_f32_e32 v6, v6, v118
	v_div_fixup_f32 v7, v7, v8, v87
	v_mul_f32_e32 v6, v7, v6
	v_add_f32_e32 v7, 1.0, v9
	v_div_scale_f32 v8, s[4:5], v7, v7, v84
	v_rcp_f32_e32 v9, v8
	v_cvt_pk_bf16_f32 v6, v6, s0
	ds_write_b16 v200, v6 offset:976
	v_mul_f32_e32 v6, v50, v112
	v_fma_f32 v12, -v8, v9, 1.0
	v_fmac_f32_e32 v9, v12, v9
	v_div_scale_f32 v12, vcc, v84, v7, v84
	v_mul_f32_e32 v13, v12, v9
	v_fma_f32 v14, -v8, v13, v12
	v_fmac_f32_e32 v13, v14, v9
	v_fma_f32 v8, -v8, v13, v12
	v_div_fmas_f32 v8, v8, v9, v13
	v_mul_f32_e32 v9, 0xbfb8aa3b, v83
	v_exp_f32_e32 v9, v9
	s_waitcnt vmcnt(0)
	v_mul_f32_e32 v6, v6, v119
	v_div_fixup_f32 v7, v8, v7, v84
	v_mul_f32_e32 v6, v7, v6
	v_add_f32_e32 v7, 1.0, v9
	v_div_scale_f32 v8, s[4:5], v7, v7, v83
	v_rcp_f32_e32 v9, v8
	v_cvt_pk_bf16_f32 v6, v6, s0
	ds_write_b16 v200, v6 offset:192
	v_mul_f32_e32 v0, v0, v111
	v_fma_f32 v6, -v8, v9, 1.0
	v_fmac_f32_e32 v9, v6, v9
	v_div_scale_f32 v6, vcc, v83, v7, v83
	v_mul_f32_e32 v12, v6, v9
	v_fma_f32 v13, -v8, v12, v6
	v_fmac_f32_e32 v12, v13, v9
	v_fma_f32 v6, -v8, v12, v6
	v_mul_f32_e32 v8, 0xbfb8aa3b, v86
	v_exp_f32_e32 v8, v8
	v_div_fmas_f32 v6, v6, v9, v12
	v_mul_f32_e32 v0, v0, v119
	v_div_fixup_f32 v6, v6, v7, v83
	v_mul_f32_e32 v0, v6, v0
	v_add_f32_e32 v6, 1.0, v8
	v_div_scale_f32 v7, s[4:5], v6, v6, v86
	v_rcp_f32_e32 v8, v7
	v_cvt_pk_bf16_f32 v0, v0, s0
	ds_write_b16 v200, v0 offset:464
	v_mul_f32_e32 v0, v4, v61
	v_fma_f32 v4, -v7, v8, 1.0
	v_fmac_f32_e32 v8, v4, v8
	v_div_scale_f32 v4, vcc, v86, v6, v86
	v_mul_f32_e32 v9, v4, v8
	v_fma_f32 v12, -v7, v9, v4
	v_fmac_f32_e32 v9, v12, v8
	v_fma_f32 v4, -v7, v9, v4
	v_mul_f32_e32 v7, 0xbfb8aa3b, v85
	v_exp_f32_e32 v7, v7
	v_div_fmas_f32 v4, v4, v8, v9
	v_mul_f32_e32 v0, v0, v119
	v_div_fixup_f32 v4, v4, v6, v86
	v_mul_f32_e32 v0, v4, v0
	v_add_f32_e32 v4, 1.0, v7
	v_div_scale_f32 v6, s[4:5], v4, v4, v85
	v_rcp_f32_e32 v7, v6
	v_cvt_pk_bf16_f32 v0, v0, s0
	ds_write_b16 v200, v0 offset:736
	v_mul_f32_e32 v0, v2, v60
	v_fma_f32 v2, -v6, v7, 1.0
	v_fmac_f32_e32 v7, v2, v7
	v_div_scale_f32 v2, vcc, v85, v4, v85
	v_mul_f32_e32 v8, v2, v7
	v_fma_f32 v9, -v6, v8, v2
	v_fmac_f32_e32 v8, v9, v7
	v_fma_f32 v2, -v6, v8, v2
	v_mul_f32_e32 v6, 0xbfb8aa3b, v82
	v_exp_f32_e32 v6, v6
	v_div_fmas_f32 v2, v2, v7, v8
	v_mul_f32_e32 v0, v0, v119
	v_div_fixup_f32 v2, v2, v4, v85
	v_mul_f32_e32 v0, v2, v0
	v_add_f32_e32 v2, 1.0, v6
	v_div_scale_f32 v4, s[4:5], v2, v2, v82
	v_rcp_f32_e32 v6, v4
	v_cvt_pk_bf16_f32 v0, v0, s0
	ds_write_b16 v200, v0 offset:1008
	v_mul_f32_e32 v0, v51, v112
	v_fma_f32 v7, -v4, v6, 1.0
	v_fmac_f32_e32 v6, v7, v6
	v_div_scale_f32 v7, vcc, v82, v2, v82
	v_mul_f32_e32 v8, v7, v6
	v_fma_f32 v9, -v4, v8, v7
	v_fmac_f32_e32 v8, v9, v6
	v_fma_f32 v4, -v4, v8, v7
	v_div_fmas_f32 v4, v4, v6, v8
	v_mul_f32_e32 v6, 0xbfb8aa3b, v81
	v_exp_f32_e32 v6, v6
	s_waitcnt vmcnt(0)
; DI float b2f(unsigned b) { return __uint_as_float(b << 16); }
; DI float fexp(float x) { return __builtin_amdgcn_exp2f(x * LOG2E); }
; DI void gla_g3_block(const P& p, int cgi, int hh, char* smem) {
;     ...
;     for (int j = 0; j < 8; ++j) {
;       const int v = 16 * j + r16;
;       const float gw = p.gla_norm_w[v];
; #pragma unroll
;       for (int r = 0; r < 4; ++r) {
;         const int tok = t0 + 16 * slab + 4 * q4 + r;
;         float g = b2f(graw[j][r]);
;         float val = o[j][r] * ss[r] * gw * (g / (1.f + fexp(-g)));
;         mixin[(long)tok * 1024 + hh * 128 + v] = f2b(val);
;       }
;     }
;   }
	v_mul_f32_e32 v0, v0, v117
	v_div_fixup_f32 v2, v4, v2, v82
	v_mul_f32_e32 v0, v2, v0
	v_add_f32_e32 v2, 1.0, v6
	v_div_scale_f32 v4, s[4:5], v2, v2, v81
	v_rcp_f32_e32 v6, v4
	v_cvt_pk_bf16_f32 v0, v0, s0
	ds_write_b16 v200, v0 offset:224
	v_mul_f32_e32 v0, v1, v111
	v_fma_f32 v1, -v4, v6, 1.0
	v_fmac_f32_e32 v6, v1, v6
	v_div_scale_f32 v1, vcc, v81, v2, v81
	v_mul_f32_e32 v7, v1, v6
	v_fma_f32 v8, -v4, v7, v1
	v_fmac_f32_e32 v7, v8, v6
	v_fma_f32 v1, -v4, v7, v1
	v_mul_f32_e32 v4, 0xbfb8aa3b, v80
	v_exp_f32_e32 v4, v4
	v_div_fmas_f32 v1, v1, v6, v7
	v_mul_f32_e32 v0, v0, v117
	v_div_fixup_f32 v1, v1, v2, v81
	v_mul_f32_e32 v0, v1, v0
	v_add_f32_e32 v1, 1.0, v4
	v_div_scale_f32 v2, s[4:5], v1, v1, v80
	v_rcp_f32_e32 v4, v2
	v_cvt_pk_bf16_f32 v0, v0, s0
	ds_write_b16 v200, v0 offset:496
	v_mul_f32_e32 v0, v5, v61
	v_fma_f32 v5, -v2, v4, 1.0
	v_fmac_f32_e32 v4, v5, v4
	v_div_scale_f32 v5, vcc, v80, v1, v80
	v_mul_f32_e32 v6, v5, v4
	v_fma_f32 v7, -v2, v6, v5
	v_fmac_f32_e32 v6, v7, v4
	v_fma_f32 v2, -v2, v6, v5
	v_div_fmas_f32 v2, v2, v4, v6
	v_mul_f32_e32 v4, 0xbfb8aa3b, v34
	v_exp_f32_e32 v4, v4
	v_mul_f32_e32 v0, v0, v117
	v_div_fixup_f32 v1, v2, v1, v80
	v_mul_f32_e32 v0, v1, v0
	v_add_f32_e32 v1, 1.0, v4
	v_div_scale_f32 v2, s[4:5], v1, v1, v34
	v_rcp_f32_e32 v4, v2
	v_cvt_pk_bf16_f32 v0, v0, s0
	ds_write_b16 v200, v0 offset:768
	v_mul_f32_e32 v0, v3, v60
	v_fma_f32 v3, -v2, v4, 1.0
	v_fmac_f32_e32 v4, v3, v4
	v_div_scale_f32 v3, vcc, v34, v1, v34
	v_mul_f32_e32 v5, v3, v4
	v_fma_f32 v6, -v2, v5, v3
	v_fmac_f32_e32 v5, v6, v4
	v_fma_f32 v2, -v2, v5, v3
	v_div_fmas_f32 v2, v2, v4, v5
	v_mul_f32_e32 v0, v0, v117
	v_div_fixup_f32 v1, v2, v1, v34
	v_mul_f32_e32 v0, v1, v0
	v_cvt_pk_bf16_f32 v0, v0, s0
	ds_write_b16 v200, v0 offset:1040
	s_waitcnt lgkmcnt(0)
	ds_read_b128 v[212:215], v201
	ds_read_b128 v[216:219], v201 offset:1088
	ds_read_b128 v[220:223], v201 offset:2176
	ds_read_b128 v[224:227], v201 offset:3264
	v_add_co_u32_e32 v204, vcc, 0x2000, v202
	s_nop 1
	v_addc_co_u32_e32 v205, vcc, 0, v203, vcc
	v_add_co_u32_e32 v206, vcc, 0x4000, v202
	s_nop 1
	v_addc_co_u32_e32 v207, vcc, 0, v203, vcc
	v_add_co_u32_e32 v208, vcc, 0x6000, v202
	s_nop 1
	v_addc_co_u32_e32 v209, vcc, 0, v203, vcc
	s_waitcnt lgkmcnt(3)
	global_store_dwordx4 v[202:203], v[212:215], off
	s_waitcnt lgkmcnt(2)
	global_store_dwordx4 v[204:205], v[216:219], off
	s_waitcnt lgkmcnt(1)
	global_store_dwordx4 v[206:207], v[220:223], off
	s_waitcnt lgkmcnt(0)
	global_store_dwordx4 v[208:209], v[224:227], off
	s_branch .LBB0_568
